# row passes: wave-wide sums via v_permlane32/16_swap + DPP row rotations instead of six ds_bpermute round trips
# baseline (speedup 1.0000x reference)
; __device__ __forceinline__ float bflo(unsigned w) { return __uint_as_float(w << 16); }
; __device__ __forceinline__ float bfhi(unsigned w) { return __uint_as_float(w & 0xffff0000u); }
; __device__ __forceinline__ float wave_sum(float v) {
; #pragma unroll
;     for (int o = 32; o >= 1; o >>= 1) v += __shfl_xor(v, o);
;     return v;
; }
; __device__ __forceinline__ void rowpass(int wv, const float* xin, const bf16_t* outb, const float* g_post, const float* g_pre_next, float* xres, bf16_t* xn, int mode) { LIDS
;     ...
;             f32x4 ov[8]; float so = 0.f;
; #pragma unroll
;             for (int ip = 0; ip < 4; ++ip) { const u32x4 w = __builtin_nontemporal_load((const u32x4*)(outb + (size_t)row * DM + ip * 512 + lane * 8));
;                 ov[2 * ip][0] = bflo(w[0]); ov[2 * ip][1] = bfhi(w[0]); ov[2 * ip][2] = bflo(w[1]); ov[2 * ip][3] = bfhi(w[1]);
;                 ov[2 * ip + 1][0] = bflo(w[2]); ov[2 * ip + 1][1] = bfhi(w[2]); ov[2 * ip + 1][2] = bflo(w[3]); ov[2 * ip + 1][3] = bfhi(w[3]); }
; #pragma unroll
;             for (int i = 0; i < 8; ++i) so += ov[i][0] * ov[i][0] + ov[i][1] * ov[i][1] + ov[i][2] * ov[i][2] + ov[i][3] * ov[i][3];
;             so = wave_sum(so); const float inv = rsqrtf(so * (1.0f / DM) + EPS);
; #pragma unroll
;             for (int i = 0; i < 8; ++i) { const f32x4 xo = __builtin_nontemporal_load((const f32x4*)(xin + (size_t)row * DM + RP_OFF(i))); const f32x4 gp = *(const f32x4*)(g_post + RP_OFF(i));
;                 xv[i] = xo + ov[i] * inv * gp; }
;         }
; #pragma unroll
;         for (int i = 0; i < 8; ++i) { if (mode != 0) __builtin_nontemporal_store(xv[i], (f32x4*)(xres + (size_t)row * DM + RP_OFF(i)));
;             ss += xv[i][0] * xv[i][0] + xv[i][1] * xv[i][1] + xv[i][2] * xv[i][2] + xv[i][3] * xv[i][3]; }
.Lrp_go1:
	s_mov_b32 s8, 0
	v_lshlrev_b32_e32 v0, 16, v72
	v_and_b32_e32 v1, 0xffff0000, v72
	v_lshlrev_b32_e32 v2, 16, v73
	v_and_b32_e32 v3, 0xffff0000, v73
	v_lshlrev_b32_e32 v4, 16, v74
	v_and_b32_e32 v5, 0xffff0000, v74
	v_lshlrev_b32_e32 v6, 16, v75
	v_and_b32_e32 v7, 0xffff0000, v75
	v_lshlrev_b32_e32 v8, 16, v76
	v_and_b32_e32 v9, 0xffff0000, v76
	v_lshlrev_b32_e32 v10, 16, v77
	v_and_b32_e32 v11, 0xffff0000, v77
	v_lshlrev_b32_e32 v12, 16, v78
	v_and_b32_e32 v13, 0xffff0000, v78
	v_lshlrev_b32_e32 v14, 16, v79
	v_and_b32_e32 v15, 0xffff0000, v79
	v_lshlrev_b32_e32 v16, 16, v80
	v_and_b32_e32 v17, 0xffff0000, v80
	v_lshlrev_b32_e32 v18, 16, v81
	v_and_b32_e32 v19, 0xffff0000, v81
	v_lshlrev_b32_e32 v20, 16, v82
	v_and_b32_e32 v21, 0xffff0000, v82
	v_lshlrev_b32_e32 v22, 16, v83
	v_and_b32_e32 v23, 0xffff0000, v83
	v_lshlrev_b32_e32 v24, 16, v84
	v_and_b32_e32 v25, 0xffff0000, v84
	v_lshlrev_b32_e32 v26, 16, v85
	v_and_b32_e32 v27, 0xffff0000, v85
	v_lshlrev_b32_e32 v28, 16, v86
	v_and_b32_e32 v29, 0xffff0000, v86
	v_lshlrev_b32_e32 v30, 16, v87
	v_and_b32_e32 v31, 0xffff0000, v87
	v_mul_f32_e32 v36, v0, v0
	v_mul_f32_e32 v37, v1, v1
	v_mul_f32_e32 v38, v2, v2
	v_mul_f32_e32 v39, v3, v3
	v_fmac_f32_e32 v36, v4, v4
	v_fmac_f32_e32 v37, v5, v5
	v_fmac_f32_e32 v38, v6, v6
	v_fmac_f32_e32 v39, v7, v7
	v_fmac_f32_e32 v36, v8, v8
	v_fmac_f32_e32 v37, v9, v9
	v_fmac_f32_e32 v38, v10, v10
	v_fmac_f32_e32 v39, v11, v11
	v_fmac_f32_e32 v36, v12, v12
	v_fmac_f32_e32 v37, v13, v13
	v_fmac_f32_e32 v38, v14, v14
	v_fmac_f32_e32 v39, v15, v15
	v_fmac_f32_e32 v36, v16, v16
	v_fmac_f32_e32 v37, v17, v17
	v_fmac_f32_e32 v38, v18, v18
	v_fmac_f32_e32 v39, v19, v19
	v_fmac_f32_e32 v36, v20, v20
	v_fmac_f32_e32 v37, v21, v21
	v_fmac_f32_e32 v38, v22, v22
	v_fmac_f32_e32 v39, v23, v23
	v_fmac_f32_e32 v36, v24, v24
	v_fmac_f32_e32 v37, v25, v25
	v_fmac_f32_e32 v38, v26, v26
	v_fmac_f32_e32 v39, v27, v27
	v_fmac_f32_e32 v36, v28, v28
	v_fmac_f32_e32 v37, v29, v29
	v_fmac_f32_e32 v38, v30, v30
	v_fmac_f32_e32 v39, v31, v31
	v_add_f32_e32 v36, v36, v37
	v_add_f32_e32 v38, v38, v39
	v_add_f32_e32 v58, v36, v38
	v_mov_b32_e32 v59, v58
	s_nop 1
	v_permlane32_swap_b32_e32 v58, v59
	v_add_f32_e32 v58, v58, v59
	v_mov_b32_e32 v59, v58
	s_nop 1
	v_permlane16_swap_b32_e32 v58, v59
	v_add_f32_e32 v58, v58, v59
	s_nop 1
	v_add_f32_dpp v58, v58, v58 row_ror:8 row_mask:0xf bank_mask:0xf
	s_nop 1
	v_add_f32_dpp v58, v58, v58 row_ror:4 row_mask:0xf bank_mask:0xf
	s_nop 1
	v_add_f32_dpp v58, v58, v58 row_ror:2 row_mask:0xf bank_mask:0xf
	s_nop 1
	v_add_f32_dpp v58, v58, v58 row_ror:1 row_mask:0xf bank_mask:0xf
	s_nop 1
	v_fmamk_f32 v60, v58, 0x3a000000, v252
	v_rsq_f32_e32 v60, v60
	s_nop 0
	v_mul_f32_e32 v0, v0, v60
	v_mul_f32_e32 v1, v1, v60
	v_mul_f32_e32 v2, v2, v60
	v_mul_f32_e32 v3, v3, v60
	v_mul_f32_e32 v4, v4, v60
	v_mul_f32_e32 v5, v5, v60
	v_mul_f32_e32 v6, v6, v60
	v_mul_f32_e32 v7, v7, v60
	v_mul_f32_e32 v8, v8, v60
	v_mul_f32_e32 v9, v9, v60
	v_mul_f32_e32 v10, v10, v60
	v_mul_f32_e32 v11, v11, v60
	v_mul_f32_e32 v12, v12, v60
	v_mul_f32_e32 v13, v13, v60
	v_mul_f32_e32 v14, v14, v60
	v_mul_f32_e32 v15, v15, v60
	v_mul_f32_e32 v16, v16, v60
	v_mul_f32_e32 v17, v17, v60
	v_mul_f32_e32 v18, v18, v60
	v_mul_f32_e32 v19, v19, v60
	v_mul_f32_e32 v20, v20, v60
	v_mul_f32_e32 v21, v21, v60
	v_mul_f32_e32 v22, v22, v60
	v_mul_f32_e32 v23, v23, v60
	v_mul_f32_e32 v24, v24, v60
	v_mul_f32_e32 v25, v25, v60
	v_mul_f32_e32 v26, v26, v60
	v_mul_f32_e32 v27, v27, v60
	v_mul_f32_e32 v28, v28, v60
	v_mul_f32_e32 v29, v29, v60
	v_mul_f32_e32 v30, v30, v60
	v_mul_f32_e32 v31, v31, v60
	v_fmac_f32_e32 v88, v178, v0
	v_fmac_f32_e32 v89, v179, v1
	v_fmac_f32_e32 v90, v180, v2
	v_fmac_f32_e32 v91, v181, v3
	v_fmac_f32_e32 v92, v182, v4
	v_fmac_f32_e32 v93, v183, v5
	v_fmac_f32_e32 v94, v184, v6
	v_fmac_f32_e32 v95, v185, v7
	v_fmac_f32_e32 v96, v186, v8
	v_fmac_f32_e32 v97, v187, v9
	v_fmac_f32_e32 v98, v188, v10
	v_fmac_f32_e32 v99, v189, v11
	v_fmac_f32_e32 v100, v190, v12
	v_fmac_f32_e32 v101, v191, v13
	v_fmac_f32_e32 v102, v192, v14
	v_fmac_f32_e32 v103, v193, v15
	v_fmac_f32_e32 v104, v194, v16
	v_fmac_f32_e32 v105, v195, v17
	v_fmac_f32_e32 v106, v196, v18
	v_fmac_f32_e32 v107, v197, v19
	v_fmac_f32_e32 v108, v198, v20
	v_fmac_f32_e32 v109, v199, v21
	v_fmac_f32_e32 v110, v200, v22
	v_fmac_f32_e32 v111, v201, v23
	v_fmac_f32_e32 v112, v202, v24
	v_fmac_f32_e32 v113, v203, v25
	v_fmac_f32_e32 v114, v204, v26
	v_fmac_f32_e32 v115, v205, v27
	v_fmac_f32_e32 v116, v206, v28
	v_fmac_f32_e32 v117, v207, v29
	v_fmac_f32_e32 v118, v208, v30
	v_fmac_f32_e32 v119, v209, v31
	v_lshl_add_u64 v[34:35], v[56:57], 0, s[16:17]
	global_store_dwordx4 v[56:57], v[88:91], off offset:0 nt
	global_store_dwordx4 v[56:57], v[92:95], off offset:16 nt
	global_store_dwordx4 v[56:57], v[96:99], off offset:2048 nt
	global_store_dwordx4 v[56:57], v[100:103], off offset:2064 nt
	global_store_dwordx4 v[34:35], v[104:107], off offset:0 nt
	global_store_dwordx4 v[34:35], v[108:111], off offset:16 nt
	global_store_dwordx4 v[34:35], v[112:115], off offset:2048 nt
	global_store_dwordx4 v[34:35], v[116:119], off offset:2064 nt
	v_lshl_add_u64 v[56:57], v[56:57], 0, s[72:73]
	s_andn2_b64 vcc, exec, s[10:11]
	s_cbranch_vccnz .Lrp_nopre1
; __device__ __forceinline__ u32x4 pack8(f32x4 a, f32x4 b) { u32x4 r; r[0] = cvt_pk_bf16(a[0], a[1]); r[1] = cvt_pk_bf16(a[2], a[3]); r[2] = cvt_pk_bf16(b[0], b[1]); r[3] = cvt_pk_bf16(b[2], b[3]); return r; }
; __device__ __forceinline__ void rowpass(int wv, const float* xin, const bf16_t* outb, const float* g_post, const float* g_pre_next, float* xres, bf16_t* xn, int mode) { LIDS
;     ...
;         if (g_pre_next) {
;             ss = wave_sum(ss); const float inv = rsqrtf(ss * (1.0f / DM) + EPS);
; #pragma unroll
;             for (int ip = 0; ip < 4; ++ip) { const f32x4 g0 = *(const f32x4*)(g_pre_next + RP_OFF(2 * ip)), g1 = *(const f32x4*)(g_pre_next + RP_OFF(2 * ip + 1));
;                 const f32x4 y0 = xv[2 * ip] * inv * g0, y1 = xv[2 * ip + 1] * inv * g1;
;                 *(u32x4*)(xn + (size_t)row * DM + ip * 512 + lane * 8) = pack8(y0, y1); }
;         }
	v_mul_f32_e32 v36, v88, v88
	v_mul_f32_e32 v37, v89, v89
	v_mul_f32_e32 v38, v90, v90
	v_mul_f32_e32 v39, v91, v91
	v_fmac_f32_e32 v36, v92, v92
	v_fmac_f32_e32 v37, v93, v93
	v_fmac_f32_e32 v38, v94, v94
	v_fmac_f32_e32 v39, v95, v95
	v_fmac_f32_e32 v36, v96, v96
	v_fmac_f32_e32 v37, v97, v97
	v_fmac_f32_e32 v38, v98, v98
	v_fmac_f32_e32 v39, v99, v99
	v_fmac_f32_e32 v36, v100, v100
	v_fmac_f32_e32 v37, v101, v101
	v_fmac_f32_e32 v38, v102, v102
	v_fmac_f32_e32 v39, v103, v103
	v_fmac_f32_e32 v36, v104, v104
	v_fmac_f32_e32 v37, v105, v105
	v_fmac_f32_e32 v38, v106, v106
	v_fmac_f32_e32 v39, v107, v107
	v_fmac_f32_e32 v36, v108, v108
	v_fmac_f32_e32 v37, v109, v109
	v_fmac_f32_e32 v38, v110, v110
	v_fmac_f32_e32 v39, v111, v111
	v_fmac_f32_e32 v36, v112, v112
	v_fmac_f32_e32 v37, v113, v113
	v_fmac_f32_e32 v38, v114, v114
	v_fmac_f32_e32 v39, v115, v115
	v_fmac_f32_e32 v36, v116, v116
	v_fmac_f32_e32 v37, v117, v117
	v_fmac_f32_e32 v38, v118, v118
	v_fmac_f32_e32 v39, v119, v119
	v_add_f32_e32 v36, v36, v37
	v_add_f32_e32 v38, v38, v39
	v_add_f32_e32 v58, v36, v38
	v_mov_b32_e32 v59, v58
	s_nop 1
	v_permlane32_swap_b32_e32 v58, v59
	v_add_f32_e32 v58, v58, v59
	v_mov_b32_e32 v59, v58
	s_nop 1
	v_permlane16_swap_b32_e32 v58, v59
	v_add_f32_e32 v58, v58, v59
	s_nop 1
	v_add_f32_dpp v58, v58, v58 row_ror:8 row_mask:0xf bank_mask:0xf
	s_nop 1
	v_add_f32_dpp v58, v58, v58 row_ror:4 row_mask:0xf bank_mask:0xf
	s_nop 1
	v_add_f32_dpp v58, v58, v58 row_ror:2 row_mask:0xf bank_mask:0xf
	s_nop 1
	v_add_f32_dpp v58, v58, v58 row_ror:1 row_mask:0xf bank_mask:0xf
	s_nop 1
	v_fmamk_f32 v60, v58, 0x3a000000, v252
	v_rsq_f32_e32 v60, v60
	s_nop 0
	v_mul_f32_e32 v168, v88, v60
	v_mul_f32_e32 v169, v89, v60
	v_mul_f32_e32 v170, v90, v60
	v_mul_f32_e32 v171, v91, v60
	v_mul_f32_e32 v172, v92, v60
	v_mul_f32_e32 v173, v93, v60
	v_mul_f32_e32 v174, v94, v60
	v_mul_f32_e32 v175, v95, v60
	v_mul_f32_e32 v168, v168, v218
	v_mul_f32_e32 v169, v169, v219
	v_mul_f32_e32 v170, v170, v220
	v_mul_f32_e32 v171, v171, v221
	v_mul_f32_e32 v172, v172, v222
	v_mul_f32_e32 v173, v173, v223
	v_mul_f32_e32 v174, v174, v224
	v_mul_f32_e32 v175, v175, v225
	v_cvt_pk_bf16_f32 v72, v168, v169
	v_cvt_pk_bf16_f32 v73, v170, v171
	v_cvt_pk_bf16_f32 v74, v172, v173
	v_cvt_pk_bf16_f32 v75, v174, v175
	v_mul_f32_e32 v168, v96, v60
	v_mul_f32_e32 v169, v97, v60
	v_mul_f32_e32 v170, v98, v60
	v_mul_f32_e32 v171, v99, v60
	v_mul_f32_e32 v172, v100, v60
	v_mul_f32_e32 v173, v101, v60
	v_mul_f32_e32 v174, v102, v60
	v_mul_f32_e32 v175, v103, v60
	v_mul_f32_e32 v168, v168, v226
	v_mul_f32_e32 v169, v169, v227
	v_mul_f32_e32 v170, v170, v228
	v_mul_f32_e32 v171, v171, v229
	v_mul_f32_e32 v172, v172, v230
	v_mul_f32_e32 v173, v173, v231
	v_mul_f32_e32 v174, v174, v232
	v_mul_f32_e32 v175, v175, v233
	v_cvt_pk_bf16_f32 v76, v168, v169
	v_cvt_pk_bf16_f32 v77, v170, v171
	v_cvt_pk_bf16_f32 v78, v172, v173
	v_cvt_pk_bf16_f32 v79, v174, v175
	v_mul_f32_e32 v168, v104, v60
	v_mul_f32_e32 v169, v105, v60
	v_mul_f32_e32 v170, v106, v60
	v_mul_f32_e32 v171, v107, v60
	v_mul_f32_e32 v172, v108, v60
	v_mul_f32_e32 v173, v109, v60
	v_mul_f32_e32 v174, v110, v60
	v_mul_f32_e32 v175, v111, v60
	v_mul_f32_e32 v168, v168, v234
	v_mul_f32_e32 v169, v169, v235
	v_mul_f32_e32 v170, v170, v236
	v_mul_f32_e32 v171, v171, v237
	v_mul_f32_e32 v172, v172, v238
	v_mul_f32_e32 v173, v173, v239
	v_mul_f32_e32 v174, v174, v240
	v_mul_f32_e32 v175, v175, v241
	v_cvt_pk_bf16_f32 v80, v168, v169
	v_cvt_pk_bf16_f32 v81, v170, v171
	v_cvt_pk_bf16_f32 v82, v172, v173
	v_cvt_pk_bf16_f32 v83, v174, v175
	v_mul_f32_e32 v168, v112, v60
	v_mul_f32_e32 v169, v113, v60
	v_mul_f32_e32 v170, v114, v60
	v_mul_f32_e32 v171, v115, v60
	v_mul_f32_e32 v172, v116, v60
	v_mul_f32_e32 v173, v117, v60
	v_mul_f32_e32 v174, v118, v60
	v_mul_f32_e32 v175, v119, v60
	v_mul_f32_e32 v168, v168, v242
	v_mul_f32_e32 v169, v169, v243
	v_mul_f32_e32 v170, v170, v244
	v_mul_f32_e32 v171, v171, v245
	v_mul_f32_e32 v172, v172, v246
	v_mul_f32_e32 v173, v173, v247
	v_mul_f32_e32 v174, v174, v248
	v_mul_f32_e32 v175, v175, v249
	v_cvt_pk_bf16_f32 v84, v168, v169
	v_cvt_pk_bf16_f32 v85, v170, v171
	v_cvt_pk_bf16_f32 v86, v172, v173
	v_cvt_pk_bf16_f32 v87, v174, v175
	global_store_dwordx4 v[32:33], v[72:75], off offset:0
	global_store_dwordx4 v[32:33], v[76:79], off offset:1024
	global_store_dwordx4 v[32:33], v[80:83], off offset:2048
	global_store_dwordx4 v[32:33], v[84:87], off offset:3072
	v_lshl_add_u64 v[32:33], v[32:33], 0, s[62:63]

; __device__ __forceinline__ float bflo(unsigned w) { return __uint_as_float(w << 16); }
; __device__ __forceinline__ float bfhi(unsigned w) { return __uint_as_float(w & 0xffff0000u); }
; __device__ __forceinline__ float wave_sum(float v) {
; #pragma unroll
;     for (int o = 32; o >= 1; o >>= 1) v += __shfl_xor(v, o);
;     return v;
; }
; __device__ __forceinline__ void rowpass(int wv, const float* xin, const bf16_t* outb, const float* g_post, const float* g_pre_next, float* xres, bf16_t* xn, int mode) { LIDS
;     ...
;             f32x4 ov[8]; float so = 0.f;
; #pragma unroll
;             for (int ip = 0; ip < 4; ++ip) { const u32x4 w = __builtin_nontemporal_load((const u32x4*)(outb + (size_t)row * DM + ip * 512 + lane * 8));
;                 ov[2 * ip][0] = bflo(w[0]); ov[2 * ip][1] = bfhi(w[0]); ov[2 * ip][2] = bflo(w[1]); ov[2 * ip][3] = bfhi(w[1]);
;                 ov[2 * ip + 1][0] = bflo(w[2]); ov[2 * ip + 1][1] = bfhi(w[2]); ov[2 * ip + 1][2] = bflo(w[3]); ov[2 * ip + 1][3] = bfhi(w[3]); }
; #pragma unroll
;             for (int i = 0; i < 8; ++i) so += ov[i][0] * ov[i][0] + ov[i][1] * ov[i][1] + ov[i][2] * ov[i][2] + ov[i][3] * ov[i][3];
;             so = wave_sum(so); const float inv = rsqrtf(so * (1.0f / DM) + EPS);
; #pragma unroll
;             for (int i = 0; i < 8; ++i) { const f32x4 xo = __builtin_nontemporal_load((const f32x4*)(xin + (size_t)row * DM + RP_OFF(i))); const f32x4 gp = *(const f32x4*)(g_post + RP_OFF(i));
;                 xv[i] = xo + ov[i] * inv * gp; }
;         }
; #pragma unroll
;         for (int i = 0; i < 8; ++i) { if (mode != 0) __builtin_nontemporal_store(xv[i], (f32x4*)(xres + (size_t)row * DM + RP_OFF(i)));
;             ss += xv[i][0] * xv[i][0] + xv[i][1] * xv[i][1] + xv[i][2] * xv[i][2] + xv[i][3] * xv[i][3]; }
.Lrp_go2:
	s_mov_b32 s8, 0
	v_lshlrev_b32_e32 v0, 16, v120
	v_and_b32_e32 v1, 0xffff0000, v120
	v_lshlrev_b32_e32 v2, 16, v121
	v_and_b32_e32 v3, 0xffff0000, v121
	v_lshlrev_b32_e32 v4, 16, v122
	v_and_b32_e32 v5, 0xffff0000, v122
	v_lshlrev_b32_e32 v6, 16, v123
	v_and_b32_e32 v7, 0xffff0000, v123
	v_lshlrev_b32_e32 v8, 16, v124
	v_and_b32_e32 v9, 0xffff0000, v124
	v_lshlrev_b32_e32 v10, 16, v125
	v_and_b32_e32 v11, 0xffff0000, v125
	v_lshlrev_b32_e32 v12, 16, v126
	v_and_b32_e32 v13, 0xffff0000, v126
	v_lshlrev_b32_e32 v14, 16, v127
	v_and_b32_e32 v15, 0xffff0000, v127
	v_lshlrev_b32_e32 v16, 16, v128
	v_and_b32_e32 v17, 0xffff0000, v128
	v_lshlrev_b32_e32 v18, 16, v129
	v_and_b32_e32 v19, 0xffff0000, v129
	v_lshlrev_b32_e32 v20, 16, v130
	v_and_b32_e32 v21, 0xffff0000, v130
	v_lshlrev_b32_e32 v22, 16, v131
	v_and_b32_e32 v23, 0xffff0000, v131
	v_lshlrev_b32_e32 v24, 16, v132
	v_and_b32_e32 v25, 0xffff0000, v132
	v_lshlrev_b32_e32 v26, 16, v133
	v_and_b32_e32 v27, 0xffff0000, v133
	v_lshlrev_b32_e32 v28, 16, v134
	v_and_b32_e32 v29, 0xffff0000, v134
	v_lshlrev_b32_e32 v30, 16, v135
	v_and_b32_e32 v31, 0xffff0000, v135
	v_mul_f32_e32 v36, v0, v0
	v_mul_f32_e32 v37, v1, v1
	v_mul_f32_e32 v38, v2, v2
	v_mul_f32_e32 v39, v3, v3
	v_fmac_f32_e32 v36, v4, v4
	v_fmac_f32_e32 v37, v5, v5
	v_fmac_f32_e32 v38, v6, v6
	v_fmac_f32_e32 v39, v7, v7
	v_fmac_f32_e32 v36, v8, v8
	v_fmac_f32_e32 v37, v9, v9
	v_fmac_f32_e32 v38, v10, v10
	v_fmac_f32_e32 v39, v11, v11
	v_fmac_f32_e32 v36, v12, v12
	v_fmac_f32_e32 v37, v13, v13
	v_fmac_f32_e32 v38, v14, v14
	v_fmac_f32_e32 v39, v15, v15
	v_fmac_f32_e32 v36, v16, v16
	v_fmac_f32_e32 v37, v17, v17
	v_fmac_f32_e32 v38, v18, v18
	v_fmac_f32_e32 v39, v19, v19
	v_fmac_f32_e32 v36, v20, v20
	v_fmac_f32_e32 v37, v21, v21
	v_fmac_f32_e32 v38, v22, v22
	v_fmac_f32_e32 v39, v23, v23
	v_fmac_f32_e32 v36, v24, v24
	v_fmac_f32_e32 v37, v25, v25
	v_fmac_f32_e32 v38, v26, v26
	v_fmac_f32_e32 v39, v27, v27
	v_fmac_f32_e32 v36, v28, v28
	v_fmac_f32_e32 v37, v29, v29
	v_fmac_f32_e32 v38, v30, v30
	v_fmac_f32_e32 v39, v31, v31
	v_add_f32_e32 v36, v36, v37
	v_add_f32_e32 v38, v38, v39
	v_add_f32_e32 v58, v36, v38
	v_mov_b32_e32 v59, v58
	s_nop 1
	v_permlane32_swap_b32_e32 v58, v59
	v_add_f32_e32 v58, v58, v59
	v_mov_b32_e32 v59, v58
	s_nop 1
	v_permlane16_swap_b32_e32 v58, v59
	v_add_f32_e32 v58, v58, v59
	s_nop 1
	v_add_f32_dpp v58, v58, v58 row_ror:8 row_mask:0xf bank_mask:0xf
	s_nop 1
	v_add_f32_dpp v58, v58, v58 row_ror:4 row_mask:0xf bank_mask:0xf
	s_nop 1
	v_add_f32_dpp v58, v58, v58 row_ror:2 row_mask:0xf bank_mask:0xf
	s_nop 1
	v_add_f32_dpp v58, v58, v58 row_ror:1 row_mask:0xf bank_mask:0xf
	s_nop 1
	v_fmamk_f32 v60, v58, 0x3a000000, v252
	v_rsq_f32_e32 v60, v60
	s_nop 0
	v_mul_f32_e32 v0, v0, v60
	v_mul_f32_e32 v1, v1, v60
	v_mul_f32_e32 v2, v2, v60
	v_mul_f32_e32 v3, v3, v60
	v_mul_f32_e32 v4, v4, v60
	v_mul_f32_e32 v5, v5, v60
	v_mul_f32_e32 v6, v6, v60
	v_mul_f32_e32 v7, v7, v60
	v_mul_f32_e32 v8, v8, v60
	v_mul_f32_e32 v9, v9, v60
	v_mul_f32_e32 v10, v10, v60
	v_mul_f32_e32 v11, v11, v60
	v_mul_f32_e32 v12, v12, v60
	v_mul_f32_e32 v13, v13, v60
	v_mul_f32_e32 v14, v14, v60
	v_mul_f32_e32 v15, v15, v60
	v_mul_f32_e32 v16, v16, v60
	v_mul_f32_e32 v17, v17, v60
	v_mul_f32_e32 v18, v18, v60
	v_mul_f32_e32 v19, v19, v60
	v_mul_f32_e32 v20, v20, v60
	v_mul_f32_e32 v21, v21, v60
	v_mul_f32_e32 v22, v22, v60
	v_mul_f32_e32 v23, v23, v60
	v_mul_f32_e32 v24, v24, v60
	v_mul_f32_e32 v25, v25, v60
	v_mul_f32_e32 v26, v26, v60
	v_mul_f32_e32 v27, v27, v60
	v_mul_f32_e32 v28, v28, v60
	v_mul_f32_e32 v29, v29, v60
	v_mul_f32_e32 v30, v30, v60
	v_mul_f32_e32 v31, v31, v60
	v_fmac_f32_e32 v136, v178, v0
	v_fmac_f32_e32 v137, v179, v1
	v_fmac_f32_e32 v138, v180, v2
	v_fmac_f32_e32 v139, v181, v3
	v_fmac_f32_e32 v140, v182, v4
	v_fmac_f32_e32 v141, v183, v5
	v_fmac_f32_e32 v142, v184, v6
	v_fmac_f32_e32 v143, v185, v7
	v_fmac_f32_e32 v144, v186, v8
	v_fmac_f32_e32 v145, v187, v9
	v_fmac_f32_e32 v146, v188, v10
	v_fmac_f32_e32 v147, v189, v11
	v_fmac_f32_e32 v148, v190, v12
	v_fmac_f32_e32 v149, v191, v13
	v_fmac_f32_e32 v150, v192, v14
	v_fmac_f32_e32 v151, v193, v15
	v_fmac_f32_e32 v152, v194, v16
	v_fmac_f32_e32 v153, v195, v17
	v_fmac_f32_e32 v154, v196, v18
	v_fmac_f32_e32 v155, v197, v19
	v_fmac_f32_e32 v156, v198, v20
	v_fmac_f32_e32 v157, v199, v21
	v_fmac_f32_e32 v158, v200, v22
	v_fmac_f32_e32 v159, v201, v23
	v_fmac_f32_e32 v160, v202, v24
	v_fmac_f32_e32 v161, v203, v25
	v_fmac_f32_e32 v162, v204, v26
	v_fmac_f32_e32 v163, v205, v27
	v_fmac_f32_e32 v164, v206, v28
	v_fmac_f32_e32 v165, v207, v29
	v_fmac_f32_e32 v166, v208, v30
	v_fmac_f32_e32 v167, v209, v31
	v_lshl_add_u64 v[34:35], v[56:57], 0, s[16:17]
	global_store_dwordx4 v[56:57], v[136:139], off offset:0 nt
	global_store_dwordx4 v[56:57], v[140:143], off offset:16 nt
	global_store_dwordx4 v[56:57], v[144:147], off offset:2048 nt
	global_store_dwordx4 v[56:57], v[148:151], off offset:2064 nt
	global_store_dwordx4 v[34:35], v[152:155], off offset:0 nt
	global_store_dwordx4 v[34:35], v[156:159], off offset:16 nt
	global_store_dwordx4 v[34:35], v[160:163], off offset:2048 nt
	global_store_dwordx4 v[34:35], v[164:167], off offset:2064 nt
	v_lshl_add_u64 v[56:57], v[56:57], 0, s[72:73]
	s_andn2_b64 vcc, exec, s[10:11]
	s_cbranch_vccnz .Lrp_nopre2
; __device__ __forceinline__ u32x4 pack8(f32x4 a, f32x4 b) { u32x4 r; r[0] = cvt_pk_bf16(a[0], a[1]); r[1] = cvt_pk_bf16(a[2], a[3]); r[2] = cvt_pk_bf16(b[0], b[1]); r[3] = cvt_pk_bf16(b[2], b[3]); return r; }
; __device__ __forceinline__ void rowpass(int wv, const float* xin, const bf16_t* outb, const float* g_post, const float* g_pre_next, float* xres, bf16_t* xn, int mode) { LIDS
;     ...
;         if (g_pre_next) {
;             ss = wave_sum(ss); const float inv = rsqrtf(ss * (1.0f / DM) + EPS);
; #pragma unroll
;             for (int ip = 0; ip < 4; ++ip) { const f32x4 g0 = *(const f32x4*)(g_pre_next + RP_OFF(2 * ip)), g1 = *(const f32x4*)(g_pre_next + RP_OFF(2 * ip + 1));
;                 const f32x4 y0 = xv[2 * ip] * inv * g0, y1 = xv[2 * ip + 1] * inv * g1;
;                 *(u32x4*)(xn + (size_t)row * DM + ip * 512 + lane * 8) = pack8(y0, y1); }
;         }
	v_mul_f32_e32 v36, v136, v136
	v_mul_f32_e32 v37, v137, v137
	v_mul_f32_e32 v38, v138, v138
	v_mul_f32_e32 v39, v139, v139
	v_fmac_f32_e32 v36, v140, v140
	v_fmac_f32_e32 v37, v141, v141
	v_fmac_f32_e32 v38, v142, v142
	v_fmac_f32_e32 v39, v143, v143
	v_fmac_f32_e32 v36, v144, v144
	v_fmac_f32_e32 v37, v145, v145
	v_fmac_f32_e32 v38, v146, v146
	v_fmac_f32_e32 v39, v147, v147
	v_fmac_f32_e32 v36, v148, v148
	v_fmac_f32_e32 v37, v149, v149
	v_fmac_f32_e32 v38, v150, v150
	v_fmac_f32_e32 v39, v151, v151
	v_fmac_f32_e32 v36, v152, v152
	v_fmac_f32_e32 v37, v153, v153
	v_fmac_f32_e32 v38, v154, v154
	v_fmac_f32_e32 v39, v155, v155
	v_fmac_f32_e32 v36, v156, v156
	v_fmac_f32_e32 v37, v157, v157
	v_fmac_f32_e32 v38, v158, v158
	v_fmac_f32_e32 v39, v159, v159
	v_fmac_f32_e32 v36, v160, v160
	v_fmac_f32_e32 v37, v161, v161
	v_fmac_f32_e32 v38, v162, v162
	v_fmac_f32_e32 v39, v163, v163
	v_fmac_f32_e32 v36, v164, v164
	v_fmac_f32_e32 v37, v165, v165
	v_fmac_f32_e32 v38, v166, v166
	v_fmac_f32_e32 v39, v167, v167
	v_add_f32_e32 v36, v36, v37
	v_add_f32_e32 v38, v38, v39
	v_add_f32_e32 v58, v36, v38
	v_mov_b32_e32 v59, v58
	s_nop 1
	v_permlane32_swap_b32_e32 v58, v59
	v_add_f32_e32 v58, v58, v59
	v_mov_b32_e32 v59, v58
	s_nop 1
	v_permlane16_swap_b32_e32 v58, v59
	v_add_f32_e32 v58, v58, v59
	s_nop 1
	v_add_f32_dpp v58, v58, v58 row_ror:8 row_mask:0xf bank_mask:0xf
	s_nop 1
	v_add_f32_dpp v58, v58, v58 row_ror:4 row_mask:0xf bank_mask:0xf
	s_nop 1
	v_add_f32_dpp v58, v58, v58 row_ror:2 row_mask:0xf bank_mask:0xf
	s_nop 1
	v_add_f32_dpp v58, v58, v58 row_ror:1 row_mask:0xf bank_mask:0xf
	s_nop 1
	v_fmamk_f32 v60, v58, 0x3a000000, v252
	v_rsq_f32_e32 v60, v60
	s_nop 0
	v_mul_f32_e32 v168, v136, v60
	v_mul_f32_e32 v169, v137, v60
	v_mul_f32_e32 v170, v138, v60
	v_mul_f32_e32 v171, v139, v60
	v_mul_f32_e32 v172, v140, v60
	v_mul_f32_e32 v173, v141, v60
	v_mul_f32_e32 v174, v142, v60
	v_mul_f32_e32 v175, v143, v60
	v_mul_f32_e32 v168, v168, v218
	v_mul_f32_e32 v169, v169, v219
	v_mul_f32_e32 v170, v170, v220
	v_mul_f32_e32 v171, v171, v221
	v_mul_f32_e32 v172, v172, v222
	v_mul_f32_e32 v173, v173, v223
	v_mul_f32_e32 v174, v174, v224
	v_mul_f32_e32 v175, v175, v225
	v_cvt_pk_bf16_f32 v120, v168, v169
	v_cvt_pk_bf16_f32 v121, v170, v171
	v_cvt_pk_bf16_f32 v122, v172, v173
	v_cvt_pk_bf16_f32 v123, v174, v175
	v_mul_f32_e32 v168, v144, v60
	v_mul_f32_e32 v169, v145, v60
	v_mul_f32_e32 v170, v146, v60
	v_mul_f32_e32 v171, v147, v60
	v_mul_f32_e32 v172, v148, v60
	v_mul_f32_e32 v173, v149, v60
	v_mul_f32_e32 v174, v150, v60
	v_mul_f32_e32 v175, v151, v60
	v_mul_f32_e32 v168, v168, v226
	v_mul_f32_e32 v169, v169, v227
	v_mul_f32_e32 v170, v170, v228
	v_mul_f32_e32 v171, v171, v229
	v_mul_f32_e32 v172, v172, v230
	v_mul_f32_e32 v173, v173, v231
	v_mul_f32_e32 v174, v174, v232
	v_mul_f32_e32 v175, v175, v233
	v_cvt_pk_bf16_f32 v124, v168, v169
	v_cvt_pk_bf16_f32 v125, v170, v171
	v_cvt_pk_bf16_f32 v126, v172, v173
	v_cvt_pk_bf16_f32 v127, v174, v175
	v_mul_f32_e32 v168, v152, v60
	v_mul_f32_e32 v169, v153, v60
	v_mul_f32_e32 v170, v154, v60
	v_mul_f32_e32 v171, v155, v60
	v_mul_f32_e32 v172, v156, v60
	v_mul_f32_e32 v173, v157, v60
	v_mul_f32_e32 v174, v158, v60
	v_mul_f32_e32 v175, v159, v60
	v_mul_f32_e32 v168, v168, v234
	v_mul_f32_e32 v169, v169, v235
	v_mul_f32_e32 v170, v170, v236
	v_mul_f32_e32 v171, v171, v237
	v_mul_f32_e32 v172, v172, v238
	v_mul_f32_e32 v173, v173, v239
	v_mul_f32_e32 v174, v174, v240
	v_mul_f32_e32 v175, v175, v241
	v_cvt_pk_bf16_f32 v128, v168, v169
	v_cvt_pk_bf16_f32 v129, v170, v171
	v_cvt_pk_bf16_f32 v130, v172, v173
	v_cvt_pk_bf16_f32 v131, v174, v175
	v_mul_f32_e32 v168, v160, v60
	v_mul_f32_e32 v169, v161, v60
	v_mul_f32_e32 v170, v162, v60
	v_mul_f32_e32 v171, v163, v60
	v_mul_f32_e32 v172, v164, v60
	v_mul_f32_e32 v173, v165, v60
	v_mul_f32_e32 v174, v166, v60
	v_mul_f32_e32 v175, v167, v60
	v_mul_f32_e32 v168, v168, v242
	v_mul_f32_e32 v169, v169, v243
	v_mul_f32_e32 v170, v170, v244
	v_mul_f32_e32 v171, v171, v245
	v_mul_f32_e32 v172, v172, v246
	v_mul_f32_e32 v173, v173, v247
	v_mul_f32_e32 v174, v174, v248
	v_mul_f32_e32 v175, v175, v249
	v_cvt_pk_bf16_f32 v132, v168, v169
	v_cvt_pk_bf16_f32 v133, v170, v171
	v_cvt_pk_bf16_f32 v134, v172, v173
	v_cvt_pk_bf16_f32 v135, v174, v175
	global_store_dwordx4 v[32:33], v[120:123], off offset:0
	global_store_dwordx4 v[32:33], v[124:127], off offset:1024
	global_store_dwordx4 v[32:33], v[128:131], off offset:2048
	global_store_dwordx4 v[32:33], v[132:135], off offset:3072
	v_lshl_add_u64 v[32:33], v[32:33], 0, s[62:63]

; __device__ __forceinline__ float bflo(unsigned w) { return __uint_as_float(w << 16); }
; __device__ __forceinline__ void rowpass(int wv, const float* xin, const bf16_t* outb, const float* g_post, const float* g_pre_next, float* xres, bf16_t* xn, int mode) { LIDS
;     ...
;     for (int row = bid_l * 8 + wid; row < SEQ; row += gdim_l * 8) {
;         f32x4 xv[8]; float ss = 0.f;
;         if (mode == 0) {
; #pragma unroll
;             for (int i = 0; i < 8; ++i) xv[i] = __builtin_nontemporal_load((const f32x4*)(xin + (size_t)row * DM + RP_OFF(i)));
;         } else {
;             f32x4 ov[8]; float so = 0.f;
; #pragma unroll
;             for (int ip = 0; ip < 4; ++ip) { const u32x4 w = __builtin_nontemporal_load((const u32x4*)(outb + (size_t)row * DM + ip * 512 + lane * 8));
;                 ov[2 * ip][0] = bflo(w[0]); ov[2 * ip][1] = bfhi(w[0]); ov[2 * ip][2] = bflo(w[1]); ov[2 * ip][3] = bfhi(w[1]);
;                 ov[2 * ip + 1][0] = bflo(w[2]); ov[2 * ip + 1][1] = bfhi(w[2]); ov[2 * ip + 1][2] = bflo(w[3]); ov[2 * ip + 1][3] = bfhi(w[3]); }
; #pragma unroll
;             for (int i = 0; i < 8; ++i) so += ov[i][0] * ov[i][0] + ov[i][1] * ov[i][1] + ov[i][2] * ov[i][2] + ov[i][3] * ov[i][3];
;             so = wave_sum(so); const float inv = rsqrtf(so * (1.0f / DM) + EPS);
; #pragma unroll
;             for (int i = 0; i < 8; ++i) { const f32x4 xo = __builtin_nontemporal_load((const f32x4*)(xin + (size_t)row * DM + RP_OFF(i))); const f32x4 gp = *(const f32x4*)(g_post + RP_OFF(i));
;                 xv[i] = xo + ov[i] * inv * gp; }
;         }
; #pragma unroll
;         for (int i = 0; i < 8; ++i) { if (mode != 0) __builtin_nontemporal_store(xv[i], (f32x4*)(xres + (size_t)row * DM + RP_OFF(i)));
;             ss += xv[i][0] * xv[i][0] + xv[i][1] * xv[i][1] + xv[i][2] * xv[i][2] + xv[i][3] * xv[i][3]; }
;         if (g_pre_next) {
;             ss = wave_sum(ss); const float inv = rsqrtf(ss * (1.0f / DM) + EPS);
; #pragma unroll
;             for (int ip = 0; ip < 4; ++ip) { const f32x4 g0 = *(const f32x4*)(g_pre_next + RP_OFF(2 * ip)), g1 = *(const f32x4*)(g_pre_next + RP_OFF(2 * ip + 1));
;                 const f32x4 y0 = xv[2 * ip] * inv * g0, y1 = xv[2 * ip + 1] * inv * g1;
;                 *(u32x4*)(xn + (size_t)row * DM + ip * 512 + lane * 8) = pack8(y0, y1); }
;         }
.Lr0_go1:
	s_mov_b32 s63, 0
	v_mul_f32_e32 v170, v74, v74
	v_mul_f32_e32 v171, v75, v75
	v_mul_f32_e32 v172, v76, v76
	v_mul_f32_e32 v173, v77, v77
	v_fmac_f32_e32 v170, v78, v78
	v_fmac_f32_e32 v171, v79, v79
	v_fmac_f32_e32 v172, v80, v80
	v_fmac_f32_e32 v173, v81, v81
	v_fmac_f32_e32 v170, v82, v82
	v_fmac_f32_e32 v171, v83, v83
	v_fmac_f32_e32 v172, v84, v84
	v_fmac_f32_e32 v173, v85, v85
	v_fmac_f32_e32 v170, v86, v86
	v_fmac_f32_e32 v171, v87, v87
	v_fmac_f32_e32 v172, v88, v88
	v_fmac_f32_e32 v173, v89, v89
	v_fmac_f32_e32 v170, v90, v90
	v_fmac_f32_e32 v171, v91, v91
	v_fmac_f32_e32 v172, v92, v92
	v_fmac_f32_e32 v173, v93, v93
	v_fmac_f32_e32 v170, v94, v94
	v_fmac_f32_e32 v171, v95, v95
	v_fmac_f32_e32 v172, v96, v96
	v_fmac_f32_e32 v173, v97, v97
	v_fmac_f32_e32 v170, v98, v98
	v_fmac_f32_e32 v171, v99, v99
	v_fmac_f32_e32 v172, v100, v100
	v_fmac_f32_e32 v173, v101, v101
	v_fmac_f32_e32 v170, v102, v102
	v_fmac_f32_e32 v171, v103, v103
	v_fmac_f32_e32 v172, v104, v104
	v_fmac_f32_e32 v173, v105, v105
	v_add_f32_e32 v170, v170, v171
	v_add_f32_e32 v172, v172, v173
	v_add_f32_e32 v174, v170, v172
	v_mov_b32_e32 v175, v174
	s_nop 1
	v_permlane32_swap_b32_e32 v174, v175
	v_add_f32_e32 v174, v174, v175
	v_mov_b32_e32 v175, v174
	s_nop 1
	v_permlane16_swap_b32_e32 v174, v175
	v_add_f32_e32 v174, v174, v175
	s_nop 1
	v_add_f32_dpp v174, v174, v174 row_ror:8 row_mask:0xf bank_mask:0xf
	s_nop 1
	v_add_f32_dpp v174, v174, v174 row_ror:4 row_mask:0xf bank_mask:0xf
	s_nop 1
	v_add_f32_dpp v174, v174, v174 row_ror:2 row_mask:0xf bank_mask:0xf
	s_nop 1
	v_add_f32_dpp v174, v174, v174 row_ror:1 row_mask:0xf bank_mask:0xf
	s_nop 1
	v_fmamk_f32 v178, v174, 0x3a000000, v252
	v_rsq_f32_e32 v178, v178
	s_nop 0
	v_mul_f32_e32 v186, v74, v178
	v_mul_f32_e32 v187, v75, v178
	v_mul_f32_e32 v188, v76, v178
	v_mul_f32_e32 v189, v77, v178
	v_mul_f32_e32 v190, v78, v178
	v_mul_f32_e32 v191, v79, v178
	v_mul_f32_e32 v192, v80, v178
	v_mul_f32_e32 v193, v81, v178
	v_mul_f32_e32 v186, v186, v138
	v_mul_f32_e32 v187, v187, v139
	v_mul_f32_e32 v188, v188, v140
	v_mul_f32_e32 v189, v189, v141
	v_mul_f32_e32 v190, v190, v142
	v_mul_f32_e32 v191, v191, v143
	v_mul_f32_e32 v192, v192, v144
	v_mul_f32_e32 v193, v193, v145
	v_cvt_pk_bf16_f32 v194, v186, v187
	v_cvt_pk_bf16_f32 v195, v188, v189
	v_cvt_pk_bf16_f32 v196, v190, v191
	v_cvt_pk_bf16_f32 v197, v192, v193
	global_store_dwordx4 v[28:29], v[194:197], off offset:-3072
	v_mul_f32_e32 v186, v82, v178
	v_mul_f32_e32 v187, v83, v178
	v_mul_f32_e32 v188, v84, v178
	v_mul_f32_e32 v189, v85, v178
	v_mul_f32_e32 v190, v86, v178
	v_mul_f32_e32 v191, v87, v178
	v_mul_f32_e32 v192, v88, v178
	v_mul_f32_e32 v193, v89, v178
	v_mul_f32_e32 v186, v186, v146
	v_mul_f32_e32 v187, v187, v147
	v_mul_f32_e32 v188, v188, v148
	v_mul_f32_e32 v189, v189, v149
	v_mul_f32_e32 v190, v190, v150
	v_mul_f32_e32 v191, v191, v151
	v_mul_f32_e32 v192, v192, v152
	v_mul_f32_e32 v193, v193, v153
	v_cvt_pk_bf16_f32 v194, v186, v187
	v_cvt_pk_bf16_f32 v195, v188, v189
	v_cvt_pk_bf16_f32 v196, v190, v191
	v_cvt_pk_bf16_f32 v197, v192, v193
	global_store_dwordx4 v[28:29], v[194:197], off offset:-2048
	v_mul_f32_e32 v186, v90, v178
	v_mul_f32_e32 v187, v91, v178
	v_mul_f32_e32 v188, v92, v178
	v_mul_f32_e32 v189, v93, v178
	v_mul_f32_e32 v190, v94, v178
	v_mul_f32_e32 v191, v95, v178
	v_mul_f32_e32 v192, v96, v178
	v_mul_f32_e32 v193, v97, v178
	v_mul_f32_e32 v186, v186, v154
	v_mul_f32_e32 v187, v187, v155
	v_mul_f32_e32 v188, v188, v156
	v_mul_f32_e32 v189, v189, v157
	v_mul_f32_e32 v190, v190, v158
	v_mul_f32_e32 v191, v191, v159
	v_mul_f32_e32 v192, v192, v160
	v_mul_f32_e32 v193, v193, v161
	v_cvt_pk_bf16_f32 v194, v186, v187
	v_cvt_pk_bf16_f32 v195, v188, v189
	v_cvt_pk_bf16_f32 v196, v190, v191
	v_cvt_pk_bf16_f32 v197, v192, v193
	global_store_dwordx4 v[28:29], v[194:197], off offset:-1024
	v_mul_f32_e32 v186, v98, v178
	v_mul_f32_e32 v187, v99, v178
	v_mul_f32_e32 v188, v100, v178
	v_mul_f32_e32 v189, v101, v178
	v_mul_f32_e32 v190, v102, v178
	v_mul_f32_e32 v191, v103, v178
	v_mul_f32_e32 v192, v104, v178
	v_mul_f32_e32 v193, v105, v178
	v_mul_f32_e32 v186, v186, v162
	v_mul_f32_e32 v187, v187, v163
	v_mul_f32_e32 v188, v188, v164
	v_mul_f32_e32 v189, v189, v165
	v_mul_f32_e32 v190, v190, v166
	v_mul_f32_e32 v191, v191, v167
	v_mul_f32_e32 v192, v192, v168
	v_mul_f32_e32 v193, v193, v169
	v_cvt_pk_bf16_f32 v194, v186, v187
	v_cvt_pk_bf16_f32 v195, v188, v189
	v_cvt_pk_bf16_f32 v196, v190, v191
	v_cvt_pk_bf16_f32 v197, v192, v193
	global_store_dwordx4 v[28:29], v[194:197], off
	v_lshl_add_u64 v[28:29], v[28:29], 0, s[12:13]
	s_cmp_gt_i32 s62, s96
	s_cbranch_scc1 .Lr0_done
	s_add_i32 s62, s62, s8
	s_cmp_gt_i32 s62, s96
	s_cbranch_scc1 .Lr0_last2
	v_lshl_add_u64 v[26:27], v[26:27], 0, s[10:11]
	global_load_dwordx4 v[74:77], v[26:27], off offset:-4096 nt
	global_load_dwordx4 v[78:81], v[26:27], off offset:-4080 nt
	global_load_dwordx4 v[82:85], v[26:27], off offset:-2048 nt
	global_load_dwordx4 v[86:89], v[26:27], off offset:-2032 nt
	global_load_dwordx4 v[90:93], v[26:27], off nt
	global_load_dwordx4 v[94:97], v[26:27], off offset:16 nt
	global_load_dwordx4 v[98:101], v[26:27], off offset:2048 nt
	global_load_dwordx4 v[102:105], v[26:27], off offset:2064 nt
	s_cmp_lg_u32 s63, 0
	s_cbranch_scc1 .Lr0_f2
	s_waitcnt vmcnt(12)
	s_branch .Lr0_go2

; __device__ __forceinline__ float bflo(unsigned w) { return __uint_as_float(w << 16); }
; __device__ __forceinline__ void rowpass(int wv, const float* xin, const bf16_t* outb, const float* g_post, const float* g_pre_next, float* xres, bf16_t* xn, int mode) { LIDS
;     ...
;     for (int row = bid_l * 8 + wid; row < SEQ; row += gdim_l * 8) {
;         f32x4 xv[8]; float ss = 0.f;
;         if (mode == 0) {
; #pragma unroll
;             for (int i = 0; i < 8; ++i) xv[i] = __builtin_nontemporal_load((const f32x4*)(xin + (size_t)row * DM + RP_OFF(i)));
;         } else {
;             f32x4 ov[8]; float so = 0.f;
; #pragma unroll
;             for (int ip = 0; ip < 4; ++ip) { const u32x4 w = __builtin_nontemporal_load((const u32x4*)(outb + (size_t)row * DM + ip * 512 + lane * 8));
;                 ov[2 * ip][0] = bflo(w[0]); ov[2 * ip][1] = bfhi(w[0]); ov[2 * ip][2] = bflo(w[1]); ov[2 * ip][3] = bfhi(w[1]);
;                 ov[2 * ip + 1][0] = bflo(w[2]); ov[2 * ip + 1][1] = bfhi(w[2]); ov[2 * ip + 1][2] = bflo(w[3]); ov[2 * ip + 1][3] = bfhi(w[3]); }
; #pragma unroll
;             for (int i = 0; i < 8; ++i) so += ov[i][0] * ov[i][0] + ov[i][1] * ov[i][1] + ov[i][2] * ov[i][2] + ov[i][3] * ov[i][3];
;             so = wave_sum(so); const float inv = rsqrtf(so * (1.0f / DM) + EPS);
; #pragma unroll
;             for (int i = 0; i < 8; ++i) { const f32x4 xo = __builtin_nontemporal_load((const f32x4*)(xin + (size_t)row * DM + RP_OFF(i))); const f32x4 gp = *(const f32x4*)(g_post + RP_OFF(i));
;                 xv[i] = xo + ov[i] * inv * gp; }
;         }
; #pragma unroll
;         for (int i = 0; i < 8; ++i) { if (mode != 0) __builtin_nontemporal_store(xv[i], (f32x4*)(xres + (size_t)row * DM + RP_OFF(i)));
;             ss += xv[i][0] * xv[i][0] + xv[i][1] * xv[i][1] + xv[i][2] * xv[i][2] + xv[i][3] * xv[i][3]; }
;         if (g_pre_next) {
;             ss = wave_sum(ss); const float inv = rsqrtf(ss * (1.0f / DM) + EPS);
; #pragma unroll
;             for (int ip = 0; ip < 4; ++ip) { const f32x4 g0 = *(const f32x4*)(g_pre_next + RP_OFF(2 * ip)), g1 = *(const f32x4*)(g_pre_next + RP_OFF(2 * ip + 1));
;                 const f32x4 y0 = xv[2 * ip] * inv * g0, y1 = xv[2 * ip + 1] * inv * g1;
;                 *(u32x4*)(xn + (size_t)row * DM + ip * 512 + lane * 8) = pack8(y0, y1); }
;         }
.Lr0_go2:
	s_mov_b32 s63, 0
	v_mul_f32_e32 v170, v106, v106
	v_mul_f32_e32 v171, v107, v107
	v_mul_f32_e32 v172, v108, v108
	v_mul_f32_e32 v173, v109, v109
	v_fmac_f32_e32 v170, v110, v110
	v_fmac_f32_e32 v171, v111, v111
	v_fmac_f32_e32 v172, v112, v112
	v_fmac_f32_e32 v173, v113, v113
	v_fmac_f32_e32 v170, v114, v114
	v_fmac_f32_e32 v171, v115, v115
	v_fmac_f32_e32 v172, v116, v116
	v_fmac_f32_e32 v173, v117, v117
	v_fmac_f32_e32 v170, v118, v118
	v_fmac_f32_e32 v171, v119, v119
	v_fmac_f32_e32 v172, v120, v120
	v_fmac_f32_e32 v173, v121, v121
	v_fmac_f32_e32 v170, v122, v122
	v_fmac_f32_e32 v171, v123, v123
	v_fmac_f32_e32 v172, v124, v124
	v_fmac_f32_e32 v173, v125, v125
	v_fmac_f32_e32 v170, v126, v126
	v_fmac_f32_e32 v171, v127, v127
	v_fmac_f32_e32 v172, v128, v128
	v_fmac_f32_e32 v173, v129, v129
	v_fmac_f32_e32 v170, v130, v130
	v_fmac_f32_e32 v171, v131, v131
	v_fmac_f32_e32 v172, v132, v132
	v_fmac_f32_e32 v173, v133, v133
	v_fmac_f32_e32 v170, v134, v134
	v_fmac_f32_e32 v171, v135, v135
	v_fmac_f32_e32 v172, v136, v136
	v_fmac_f32_e32 v173, v137, v137
	v_add_f32_e32 v170, v170, v171
	v_add_f32_e32 v172, v172, v173
	v_add_f32_e32 v174, v170, v172
	v_mov_b32_e32 v175, v174
	s_nop 1
	v_permlane32_swap_b32_e32 v174, v175
	v_add_f32_e32 v174, v174, v175
	v_mov_b32_e32 v175, v174
	s_nop 1
	v_permlane16_swap_b32_e32 v174, v175
	v_add_f32_e32 v174, v174, v175
	s_nop 1
	v_add_f32_dpp v174, v174, v174 row_ror:8 row_mask:0xf bank_mask:0xf
	s_nop 1
	v_add_f32_dpp v174, v174, v174 row_ror:4 row_mask:0xf bank_mask:0xf
	s_nop 1
	v_add_f32_dpp v174, v174, v174 row_ror:2 row_mask:0xf bank_mask:0xf
	s_nop 1
	v_add_f32_dpp v174, v174, v174 row_ror:1 row_mask:0xf bank_mask:0xf
	s_nop 1
	v_fmamk_f32 v178, v174, 0x3a000000, v252
	v_rsq_f32_e32 v178, v178
	s_nop 0
	v_mul_f32_e32 v186, v106, v178
	v_mul_f32_e32 v187, v107, v178
	v_mul_f32_e32 v188, v108, v178
	v_mul_f32_e32 v189, v109, v178
	v_mul_f32_e32 v190, v110, v178
	v_mul_f32_e32 v191, v111, v178
	v_mul_f32_e32 v192, v112, v178
	v_mul_f32_e32 v193, v113, v178
	v_mul_f32_e32 v186, v186, v138
	v_mul_f32_e32 v187, v187, v139
	v_mul_f32_e32 v188, v188, v140
	v_mul_f32_e32 v189, v189, v141
	v_mul_f32_e32 v190, v190, v142
	v_mul_f32_e32 v191, v191, v143
	v_mul_f32_e32 v192, v192, v144
	v_mul_f32_e32 v193, v193, v145
	v_cvt_pk_bf16_f32 v194, v186, v187
	v_cvt_pk_bf16_f32 v195, v188, v189
	v_cvt_pk_bf16_f32 v196, v190, v191
	v_cvt_pk_bf16_f32 v197, v192, v193
	global_store_dwordx4 v[28:29], v[194:197], off offset:-3072
	v_mul_f32_e32 v186, v114, v178
	v_mul_f32_e32 v187, v115, v178
	v_mul_f32_e32 v188, v116, v178
	v_mul_f32_e32 v189, v117, v178
	v_mul_f32_e32 v190, v118, v178
	v_mul_f32_e32 v191, v119, v178
	v_mul_f32_e32 v192, v120, v178
	v_mul_f32_e32 v193, v121, v178
	v_mul_f32_e32 v186, v186, v146
	v_mul_f32_e32 v187, v187, v147
	v_mul_f32_e32 v188, v188, v148
	v_mul_f32_e32 v189, v189, v149
	v_mul_f32_e32 v190, v190, v150
	v_mul_f32_e32 v191, v191, v151
	v_mul_f32_e32 v192, v192, v152
	v_mul_f32_e32 v193, v193, v153
	v_cvt_pk_bf16_f32 v194, v186, v187
	v_cvt_pk_bf16_f32 v195, v188, v189
	v_cvt_pk_bf16_f32 v196, v190, v191
	v_cvt_pk_bf16_f32 v197, v192, v193
	global_store_dwordx4 v[28:29], v[194:197], off offset:-2048
	v_mul_f32_e32 v186, v122, v178
	v_mul_f32_e32 v187, v123, v178
	v_mul_f32_e32 v188, v124, v178
	v_mul_f32_e32 v189, v125, v178
	v_mul_f32_e32 v190, v126, v178
	v_mul_f32_e32 v191, v127, v178
	v_mul_f32_e32 v192, v128, v178
	v_mul_f32_e32 v193, v129, v178
	v_mul_f32_e32 v186, v186, v154
	v_mul_f32_e32 v187, v187, v155
	v_mul_f32_e32 v188, v188, v156
	v_mul_f32_e32 v189, v189, v157
	v_mul_f32_e32 v190, v190, v158
	v_mul_f32_e32 v191, v191, v159
	v_mul_f32_e32 v192, v192, v160
	v_mul_f32_e32 v193, v193, v161
	v_cvt_pk_bf16_f32 v194, v186, v187
	v_cvt_pk_bf16_f32 v195, v188, v189
	v_cvt_pk_bf16_f32 v196, v190, v191
	v_cvt_pk_bf16_f32 v197, v192, v193
	global_store_dwordx4 v[28:29], v[194:197], off offset:-1024
	v_mul_f32_e32 v186, v130, v178
	v_mul_f32_e32 v187, v131, v178
	v_mul_f32_e32 v188, v132, v178
	v_mul_f32_e32 v189, v133, v178
	v_mul_f32_e32 v190, v134, v178
	v_mul_f32_e32 v191, v135, v178
	v_mul_f32_e32 v192, v136, v178
	v_mul_f32_e32 v193, v137, v178
	v_mul_f32_e32 v186, v186, v162
	v_mul_f32_e32 v187, v187, v163
	v_mul_f32_e32 v188, v188, v164
	v_mul_f32_e32 v189, v189, v165
	v_mul_f32_e32 v190, v190, v166
	v_mul_f32_e32 v191, v191, v167
	v_mul_f32_e32 v192, v192, v168
	v_mul_f32_e32 v193, v193, v169
	v_cvt_pk_bf16_f32 v194, v186, v187
	v_cvt_pk_bf16_f32 v195, v188, v189
	v_cvt_pk_bf16_f32 v196, v190, v191
	v_cvt_pk_bf16_f32 v197, v192, v193
	global_store_dwordx4 v[28:29], v[194:197], off
	v_lshl_add_u64 v[28:29], v[28:29], 0, s[12:13]
	s_cmp_gt_i32 s62, s96
	s_cbranch_scc1 .Lr0_done
	s_branch .Lr0_loop
